# up epilogue: half of the H stores (pattern 0101 per 4) use the default write-back policy, the other half stay nt (split the burst between L2 and the fabric), on top of v59
# baseline (speedup 1.0000x reference)
; __device__ __forceinline__ unsigned cvt_pk_bf16(float lo, float hi) { unsigned r; asm volatile("v_cvt_pk_bf16_f32 %0, %1, %2" : "=v"(r) : "v"(lo), "v"(hi)); return r; }
;     __device__ __forceinline__ void operator()(const f32x4 (&acc)[2][2][4][2], const Unit& u, int ui, int wr, int wc, int fr, int fq) const {
;         asm volatile("" : "+v"(fr), "+v"(fq));
;         if (skip) return;
;         const int row0 = u.pm * BM + wr * 64 + fr, col0 = u.pn * HALF + wc * 32 + 8 * fq;
;         float rs[2][4];
; #pragma unroll
;         for (int ai = 0; ai < 2; ++ai)
; #pragma unroll
;             for (int m = 0; m < 4; ++m) rs[ai][m] = row_rstd(lds, ui, ai * HALF + wr * 64 + m * 16 + fr);
; #pragma unroll
;         for (int ai = 0; ai < 2; ++ai)
; #pragma unroll
;             for (int m = 0; m < 4; ++m) { const float r = rs[ai][m]; const int row = row0 + ai * HALF + m * 16;
;                 const float c1 = r * -1.44269504089f, r2 = r * r; u32x4 w;
; #pragma unroll
;                 for (int n = 0; n < 2; ++n)
; #pragma unroll
;                     for (int p = 0; p < 2; ++p) { const f32x2 g = (f32x2){acc[ai][0][m][n][2 * p], acc[ai][0][m][n][2 * p + 1]}, uu = (f32x2){acc[ai][1][m][n][2 * p], acc[ai][1][m][n][2 * p + 1]};
;                         const f32x2 t = g * c1; f32x2 d; d.x = __builtin_amdgcn_exp2f(t.x); d.y = __builtin_amdgcn_exp2f(t.y); d = d + 1.0f;
;                         f32x2 q; q.x = __builtin_amdgcn_rcpf(d.x); q.y = __builtin_amdgcn_rcpf(d.y);
;                         const f32x2 hh = (g * uu) * (q * r2); w[2 * n + p] = cvt_pk_bf16(hh.x, hh.y); }
;                 __builtin_nontemporal_store(w, (u32x4*)(H + (size_t)row * ldh + col0)); }
.LBB0_449:
	v_mov_b32_e32 v140, v147
	v_mov_b32_e32 v167, v164
	v_pk_mul_f32 v[120:121], v[124:125], v[120:121]
	v_add_u32_e32 v171, s35, v140
	v_lshlrev_b32_e32 v140, 2, v171
	v_lshl_add_u32 v140, s48, 10, v140
	v_add_u32_e32 v140, 0x20400, v140
	ds_read2_b32 v[168:169], v140 offset1:16
	ds_read2_b32 v[162:163], v140 offset0:32 offset1:48
	ds_read2_b32 v[142:143], v140 offset0:128 offset1:144
	ds_read2_b32 v[140:141], v140 offset0:160 offset1:176
	v_pk_mul_f32 v[122:123], v[126:127], v[122:123]
	s_waitcnt lgkmcnt(0)
	v_mul_f32_e32 v172, 0xbfb8aa3b, v168
	v_pk_mul_f32 v[174:175], v[124:125], v[172:173] op_sel_hi:[1,0]
	v_pk_mul_f32 v[124:125], v[126:127], v[172:173] op_sel_hi:[1,0]
	v_exp_f32_e32 v174, v174
	v_exp_f32_e32 v175, v175
	v_exp_f32_e32 v124, v124
	v_exp_f32_e32 v125, v125
	v_mul_f32_e32 v168, v168, v168
	v_pk_add_f32 v[174:175], v[174:175], 1.0 op_sel_hi:[1,0]
	v_pk_mul_f32 v[112:113], v[116:117], v[112:113]
	v_rcp_f32_e32 v174, v174
	v_rcp_f32_e32 v175, v175
	v_pk_add_f32 v[124:125], v[124:125], 1.0 op_sel_hi:[1,0]
	v_pk_mul_f32 v[114:115], v[118:119], v[114:115]
	v_rcp_f32_e32 v124, v124
	v_rcp_f32_e32 v125, v125
	v_pk_mul_f32 v[126:127], v[168:169], v[174:175] op_sel_hi:[0,1]
	v_pk_mul_f32 v[120:121], v[120:121], v[126:127]
	v_pk_mul_f32 v[126:127], v[116:117], v[172:173] op_sel_hi:[1,0]
	v_pk_mul_f32 v[124:125], v[168:169], v[124:125] op_sel_hi:[0,1]
	v_exp_f32_e32 v126, v126
	v_exp_f32_e32 v127, v127
	v_pk_mul_f32 v[122:123], v[122:123], v[124:125]
	v_pk_mul_f32 v[124:125], v[118:119], v[172:173] op_sel_hi:[1,0]
	v_cvt_pk_bf16_f32 v120, v120, v121
	v_cvt_pk_bf16_f32 v121, v122, v123
	v_pk_add_f32 v[122:123], v[126:127], 1.0 op_sel_hi:[1,0]
	v_exp_f32_e32 v124, v124
	v_exp_f32_e32 v125, v125
	v_rcp_f32_e32 v122, v122
	v_rcp_f32_e32 v123, v123
	s_lshl_b32 s5, s47, 7
	v_pk_add_f32 v[116:117], v[124:125], 1.0 op_sel_hi:[1,0]
	s_or_b32 s5, s5, s36
	v_rcp_f32_e32 v116, v116
	v_rcp_f32_e32 v117, v117
	v_pk_mul_f32 v[118:119], v[168:169], v[122:123] op_sel_hi:[0,1]
	v_pk_mul_f32 v[112:113], v[112:113], v[118:119]
	v_mul_f32_e32 v118, 0xbfb8aa3b, v169
	v_cvt_pk_bf16_f32 v122, v112, v113
	v_pk_mul_f32 v[112:113], v[168:169], v[116:117] op_sel_hi:[0,1]
	v_pk_mul_f32 v[124:125], v[108:109], v[118:119] op_sel_hi:[1,0]
	v_lshl_add_u32 v170, v167, 3, s5
	v_pk_mul_f32 v[112:113], v[114:115], v[112:113]
	v_exp_f32_e32 v124, v124
	v_exp_f32_e32 v125, v125
	v_lshl_add_u32 v167, s46, 8, v171
	v_ashrrev_i32_e32 v171, 31, v170
	v_cvt_pk_bf16_f32 v123, v112, v113
	v_mov_b64_e32 v[112:113], s[20:21]
	v_pk_mul_f32 v[104:105], v[108:109], v[104:105]
	v_pk_mul_f32 v[108:109], v[110:111], v[118:119] op_sel_hi:[1,0]
	v_mad_i64_i32 v[116:117], s[14:15], v167, s59, v[112:113]
	v_lshlrev_b64 v[114:115], 1, v[170:171]
	v_exp_f32_e32 v108, v108
	v_exp_f32_e32 v109, v109
	v_lshl_add_u64 v[116:117], v[116:117], 0, v[114:115]
	global_store_dwordx4 v[116:117], v[120:123], off nt
	v_mul_f32_e32 v116, v169, v169
	v_pk_add_f32 v[108:109], v[108:109], 1.0 op_sel_hi:[1,0]
	v_pk_add_f32 v[120:121], v[124:125], 1.0 op_sel_hi:[1,0]
	v_rcp_f32_e32 v108, v108
	v_rcp_f32_e32 v120, v120
	v_rcp_f32_e32 v121, v121
	v_rcp_f32_e32 v109, v109
	v_pk_mul_f32 v[106:107], v[110:111], v[106:107]
	v_pk_mul_f32 v[96:97], v[100:101], v[96:97]
	v_pk_mul_f32 v[110:111], v[116:117], v[120:121] op_sel_hi:[0,1]
	v_pk_mul_f32 v[104:105], v[104:105], v[110:111]
	v_pk_mul_f32 v[110:111], v[100:101], v[118:119] op_sel_hi:[1,0]
	v_pk_mul_f32 v[108:109], v[116:117], v[108:109] op_sel_hi:[0,1]
	v_exp_f32_e32 v110, v110
	v_exp_f32_e32 v111, v111
	v_pk_mul_f32 v[106:107], v[106:107], v[108:109]
	v_pk_mul_f32 v[108:109], v[102:103], v[118:119] op_sel_hi:[1,0]
	v_cvt_pk_bf16_f32 v104, v104, v105
	v_cvt_pk_bf16_f32 v105, v106, v107
	v_pk_add_f32 v[106:107], v[110:111], 1.0 op_sel_hi:[1,0]
	v_exp_f32_e32 v108, v108
	v_exp_f32_e32 v109, v109
	v_rcp_f32_e32 v106, v106
	v_rcp_f32_e32 v107, v107
	v_pk_mul_f32 v[98:99], v[102:103], v[98:99]
	v_pk_add_f32 v[100:101], v[108:109], 1.0 op_sel_hi:[1,0]
	v_pk_mul_f32 v[88:89], v[92:93], v[88:89]
	v_rcp_f32_e32 v100, v100
	v_rcp_f32_e32 v101, v101
	v_pk_mul_f32 v[102:103], v[116:117], v[106:107] op_sel_hi:[0,1]
	v_pk_mul_f32 v[96:97], v[96:97], v[102:103]
	v_pk_mul_f32 v[90:91], v[94:95], v[90:91]
	v_cvt_pk_bf16_f32 v106, v96, v97
	v_pk_mul_f32 v[96:97], v[116:117], v[100:101] op_sel_hi:[0,1]
	v_pk_mul_f32 v[96:97], v[98:99], v[96:97]
	v_mul_f32_e32 v98, 0xbfb8aa3b, v162
	v_pk_mul_f32 v[100:101], v[92:93], v[98:99] op_sel_hi:[1,0]
	v_pk_mul_f32 v[92:93], v[94:95], v[98:99] op_sel_hi:[1,0]
	v_exp_f32_e32 v100, v100
	v_exp_f32_e32 v101, v101
	v_exp_f32_e32 v92, v92
	v_exp_f32_e32 v93, v93
	v_cvt_pk_bf16_f32 v107, v96, v97
	v_pk_add_f32 v[100:101], v[100:101], 1.0 op_sel_hi:[1,0]
	v_add_u32_e32 v96, 16, v167
	v_rcp_f32_e32 v100, v100
	v_rcp_f32_e32 v101, v101
	v_mad_i64_i32 v[96:97], s[14:15], v96, s59, v[112:113]
	v_pk_add_f32 v[92:93], v[92:93], 1.0 op_sel_hi:[1,0]
	v_lshl_add_u64 v[96:97], v[96:97], 0, v[114:115]
	v_rcp_f32_e32 v92, v92
	v_rcp_f32_e32 v93, v93
	global_store_dwordx4 v[96:97], v[104:107], off
	v_mul_f32_e32 v96, v162, v162
	v_pk_mul_f32 v[94:95], v[96:97], v[100:101] op_sel_hi:[0,1]
	v_pk_mul_f32 v[88:89], v[88:89], v[94:95]
	v_pk_mul_f32 v[94:95], v[84:85], v[98:99] op_sel_hi:[1,0]
	v_pk_mul_f32 v[92:93], v[96:97], v[92:93] op_sel_hi:[0,1]
	v_exp_f32_e32 v94, v94
	v_exp_f32_e32 v95, v95
	v_pk_mul_f32 v[90:91], v[90:91], v[92:93]
	v_pk_mul_f32 v[92:93], v[86:87], v[98:99] op_sel_hi:[1,0]
	v_cvt_pk_bf16_f32 v88, v88, v89
	v_cvt_pk_bf16_f32 v89, v90, v91
	v_pk_add_f32 v[90:91], v[94:95], 1.0 op_sel_hi:[1,0]
	v_exp_f32_e32 v92, v92
	v_exp_f32_e32 v93, v93
; __device__ __forceinline__ unsigned cvt_pk_bf16(float lo, float hi) { unsigned r; asm volatile("v_cvt_pk_bf16_f32 %0, %1, %2" : "=v"(r) : "v"(lo), "v"(hi)); return r; }
;     __device__ __forceinline__ void operator()(const f32x4 (&acc)[2][2][4][2], const Unit& u, int ui, int wr, int wc, int fr, int fq) const {
;     ...
;             for (int m = 0; m < 4; ++m) { const float r = rs[ai][m]; const int row = row0 + ai * HALF + m * 16;
;                 const float c1 = r * -1.44269504089f, r2 = r * r; u32x4 w;
; #pragma unroll
;                 for (int n = 0; n < 2; ++n)
; #pragma unroll
;                     for (int p = 0; p < 2; ++p) { const f32x2 g = (f32x2){acc[ai][0][m][n][2 * p], acc[ai][0][m][n][2 * p + 1]}, uu = (f32x2){acc[ai][1][m][n][2 * p], acc[ai][1][m][n][2 * p + 1]};
;                         const f32x2 t = g * c1; f32x2 d; d.x = __builtin_amdgcn_exp2f(t.x); d.y = __builtin_amdgcn_exp2f(t.y); d = d + 1.0f;
;                         f32x2 q; q.x = __builtin_amdgcn_rcpf(d.x); q.y = __builtin_amdgcn_rcpf(d.y);
;                         const f32x2 hh = (g * uu) * (q * r2); w[2 * n + p] = cvt_pk_bf16(hh.x, hh.y); }
;                 __builtin_nontemporal_store(w, (u32x4*)(H + (size_t)row * ldh + col0)); }
	v_rcp_f32_e32 v90, v90
	v_rcp_f32_e32 v91, v91
	v_pk_mul_f32 v[80:81], v[84:85], v[80:81]
	v_pk_add_f32 v[84:85], v[92:93], 1.0 op_sel_hi:[1,0]
	v_pk_mul_f32 v[82:83], v[86:87], v[82:83]
	v_rcp_f32_e32 v84, v84
	v_rcp_f32_e32 v85, v85
	v_pk_mul_f32 v[86:87], v[96:97], v[90:91] op_sel_hi:[0,1]
	v_pk_mul_f32 v[80:81], v[80:81], v[86:87]
	v_pk_mul_f32 v[72:73], v[76:77], v[72:73]
	v_cvt_pk_bf16_f32 v90, v80, v81
	v_pk_mul_f32 v[80:81], v[96:97], v[84:85] op_sel_hi:[0,1]
	v_pk_mul_f32 v[80:81], v[82:83], v[80:81]
	v_mul_f32_e32 v82, 0xbfb8aa3b, v163
	v_pk_mul_f32 v[84:85], v[76:77], v[82:83] op_sel_hi:[1,0]
	v_pk_mul_f32 v[76:77], v[78:79], v[82:83] op_sel_hi:[1,0]
	v_exp_f32_e32 v84, v84
	v_exp_f32_e32 v85, v85
	v_exp_f32_e32 v76, v76
	v_exp_f32_e32 v77, v77
	v_cvt_pk_bf16_f32 v91, v80, v81
	v_pk_add_f32 v[84:85], v[84:85], 1.0 op_sel_hi:[1,0]
	v_add_u32_e32 v80, 32, v167
	v_rcp_f32_e32 v84, v84
	v_rcp_f32_e32 v85, v85
	v_mad_i64_i32 v[80:81], s[14:15], v80, s59, v[112:113]
	v_pk_add_f32 v[76:77], v[76:77], 1.0 op_sel_hi:[1,0]
	v_lshl_add_u64 v[80:81], v[80:81], 0, v[114:115]
	v_rcp_f32_e32 v76, v76
	v_rcp_f32_e32 v77, v77
	global_store_dwordx4 v[80:81], v[88:91], off nt
	v_mul_f32_e32 v80, v163, v163
	v_pk_mul_f32 v[74:75], v[78:79], v[74:75]
	v_pk_mul_f32 v[78:79], v[80:81], v[84:85] op_sel_hi:[0,1]
	v_pk_mul_f32 v[72:73], v[72:73], v[78:79]
	v_pk_mul_f32 v[78:79], v[68:69], v[82:83] op_sel_hi:[1,0]
	v_pk_mul_f32 v[76:77], v[80:81], v[76:77] op_sel_hi:[0,1]
	v_exp_f32_e32 v78, v78
	v_exp_f32_e32 v79, v79
	v_pk_mul_f32 v[74:75], v[74:75], v[76:77]
	v_pk_mul_f32 v[76:77], v[70:71], v[82:83] op_sel_hi:[1,0]
	v_cvt_pk_bf16_f32 v72, v72, v73
	v_cvt_pk_bf16_f32 v73, v74, v75
	v_pk_add_f32 v[74:75], v[78:79], 1.0 op_sel_hi:[1,0]
	v_exp_f32_e32 v76, v76
	v_exp_f32_e32 v77, v77
	v_rcp_f32_e32 v74, v74
	v_rcp_f32_e32 v75, v75
	v_pk_mul_f32 v[64:65], v[68:69], v[64:65]
	v_pk_add_f32 v[68:69], v[76:77], 1.0 op_sel_hi:[1,0]
	v_pk_mul_f32 v[66:67], v[70:71], v[66:67]
	v_rcp_f32_e32 v68, v68
	v_rcp_f32_e32 v69, v69
	v_pk_mul_f32 v[70:71], v[80:81], v[74:75] op_sel_hi:[0,1]
	v_pk_mul_f32 v[64:65], v[64:65], v[70:71]
	v_pk_mul_f32 v[56:57], v[60:61], v[56:57]
	v_cvt_pk_bf16_f32 v74, v64, v65
	v_pk_mul_f32 v[64:65], v[80:81], v[68:69] op_sel_hi:[0,1]
	v_pk_mul_f32 v[64:65], v[66:67], v[64:65]
	v_mul_f32_e32 v66, 0xbfb8aa3b, v142
	v_pk_mul_f32 v[68:69], v[60:61], v[66:67] op_sel_hi:[1,0]
	v_pk_mul_f32 v[60:61], v[62:63], v[66:67] op_sel_hi:[1,0]
	v_exp_f32_e32 v68, v68
	v_exp_f32_e32 v69, v69
	v_exp_f32_e32 v60, v60
	v_exp_f32_e32 v61, v61
	v_cvt_pk_bf16_f32 v75, v64, v65
	v_pk_add_f32 v[68:69], v[68:69], 1.0 op_sel_hi:[1,0]
	v_add_u32_e32 v64, 48, v167
	v_rcp_f32_e32 v68, v68
	v_rcp_f32_e32 v69, v69
	v_mad_i64_i32 v[64:65], s[14:15], v64, s59, v[112:113]
	v_pk_add_f32 v[60:61], v[60:61], 1.0 op_sel_hi:[1,0]
	v_lshl_add_u64 v[64:65], v[64:65], 0, v[114:115]
	v_rcp_f32_e32 v60, v60
	v_rcp_f32_e32 v61, v61
	global_store_dwordx4 v[64:65], v[72:75], off
	v_add_u32_e32 v65, 0x80, v167
	v_mul_f32_e32 v64, v142, v142
	v_pk_mul_f32 v[58:59], v[62:63], v[58:59]
	v_pk_mul_f32 v[62:63], v[64:65], v[68:69] op_sel_hi:[0,1]
	v_pk_mul_f32 v[56:57], v[56:57], v[62:63]
	v_pk_mul_f32 v[62:63], v[52:53], v[66:67] op_sel_hi:[1,0]
	v_pk_mul_f32 v[60:61], v[64:65], v[60:61] op_sel_hi:[0,1]
	v_exp_f32_e32 v62, v62
	v_exp_f32_e32 v63, v63
	v_pk_mul_f32 v[58:59], v[58:59], v[60:61]
	v_pk_mul_f32 v[60:61], v[54:55], v[66:67] op_sel_hi:[1,0]
	v_cvt_pk_bf16_f32 v56, v56, v57
	v_cvt_pk_bf16_f32 v57, v58, v59
	v_pk_add_f32 v[58:59], v[62:63], 1.0 op_sel_hi:[1,0]
	v_exp_f32_e32 v60, v60
	v_exp_f32_e32 v61, v61
	v_rcp_f32_e32 v58, v58
	v_rcp_f32_e32 v59, v59
	v_pk_mul_f32 v[48:49], v[52:53], v[48:49]
	v_pk_add_f32 v[52:53], v[60:61], 1.0 op_sel_hi:[1,0]
	v_pk_mul_f32 v[50:51], v[54:55], v[50:51]
	v_rcp_f32_e32 v52, v52
	v_rcp_f32_e32 v53, v53
	v_pk_mul_f32 v[54:55], v[64:65], v[58:59] op_sel_hi:[0,1]
	v_pk_mul_f32 v[48:49], v[48:49], v[54:55]
	v_pk_mul_f32 v[40:41], v[44:45], v[40:41]
	v_cvt_pk_bf16_f32 v58, v48, v49
	v_pk_mul_f32 v[48:49], v[64:65], v[52:53] op_sel_hi:[0,1]
	v_pk_mul_f32 v[48:49], v[50:51], v[48:49]
	v_mul_f32_e32 v50, 0xbfb8aa3b, v143
	v_pk_mul_f32 v[52:53], v[44:45], v[50:51] op_sel_hi:[1,0]
	v_pk_mul_f32 v[44:45], v[46:47], v[50:51] op_sel_hi:[1,0]
	v_exp_f32_e32 v52, v52
	v_exp_f32_e32 v53, v53
	v_exp_f32_e32 v44, v44
	v_exp_f32_e32 v45, v45
	v_cvt_pk_bf16_f32 v59, v48, v49
	v_pk_add_f32 v[52:53], v[52:53], 1.0 op_sel_hi:[1,0]
	v_mad_i64_i32 v[48:49], s[14:15], v65, s59, v[112:113]
	v_rcp_f32_e32 v52, v52
	v_rcp_f32_e32 v53, v53
	v_pk_add_f32 v[44:45], v[44:45], 1.0 op_sel_hi:[1,0]
	v_lshl_add_u64 v[48:49], v[48:49], 0, v[114:115]
	v_rcp_f32_e32 v44, v44
	v_rcp_f32_e32 v45, v45
	global_store_dwordx4 v[48:49], v[56:59], off nt
	v_mul_f32_e32 v48, v143, v143
	v_pk_mul_f32 v[42:43], v[46:47], v[42:43]
	v_pk_mul_f32 v[46:47], v[48:49], v[52:53] op_sel_hi:[0,1]
; __device__ __forceinline__ unsigned cvt_pk_bf16(float lo, float hi) { unsigned r; asm volatile("v_cvt_pk_bf16_f32 %0, %1, %2" : "=v"(r) : "v"(lo), "v"(hi)); return r; }
;     __device__ __forceinline__ void operator()(const f32x4 (&acc)[2][2][4][2], const Unit& u, int ui, int wr, int wc, int fr, int fq) const {
;     ...
;             for (int m = 0; m < 4; ++m) { const float r = rs[ai][m]; const int row = row0 + ai * HALF + m * 16;
;                 const float c1 = r * -1.44269504089f, r2 = r * r; u32x4 w;
; #pragma unroll
;                 for (int n = 0; n < 2; ++n)
; #pragma unroll
;                     for (int p = 0; p < 2; ++p) { const f32x2 g = (f32x2){acc[ai][0][m][n][2 * p], acc[ai][0][m][n][2 * p + 1]}, uu = (f32x2){acc[ai][1][m][n][2 * p], acc[ai][1][m][n][2 * p + 1]};
;                         const f32x2 t = g * c1; f32x2 d; d.x = __builtin_amdgcn_exp2f(t.x); d.y = __builtin_amdgcn_exp2f(t.y); d = d + 1.0f;
;                         f32x2 q; q.x = __builtin_amdgcn_rcpf(d.x); q.y = __builtin_amdgcn_rcpf(d.y);
;                         const f32x2 hh = (g * uu) * (q * r2); w[2 * n + p] = cvt_pk_bf16(hh.x, hh.y); }
;                 __builtin_nontemporal_store(w, (u32x4*)(H + (size_t)row * ldh + col0)); }
	v_pk_mul_f32 v[40:41], v[40:41], v[46:47]
	v_pk_mul_f32 v[46:47], v[36:37], v[50:51] op_sel_hi:[1,0]
	v_pk_mul_f32 v[44:45], v[48:49], v[44:45] op_sel_hi:[0,1]
	v_exp_f32_e32 v46, v46
	v_exp_f32_e32 v47, v47
	v_pk_mul_f32 v[42:43], v[42:43], v[44:45]
	v_pk_mul_f32 v[44:45], v[38:39], v[50:51] op_sel_hi:[1,0]
	v_cvt_pk_bf16_f32 v40, v40, v41
	v_cvt_pk_bf16_f32 v41, v42, v43
	v_pk_add_f32 v[42:43], v[46:47], 1.0 op_sel_hi:[1,0]
	v_exp_f32_e32 v44, v44
	v_exp_f32_e32 v45, v45
	v_rcp_f32_e32 v42, v42
	v_rcp_f32_e32 v43, v43
	v_pk_mul_f32 v[32:33], v[36:37], v[32:33]
	v_pk_add_f32 v[36:37], v[44:45], 1.0 op_sel_hi:[1,0]
	v_pk_mul_f32 v[34:35], v[38:39], v[34:35]
	v_rcp_f32_e32 v36, v36
	v_rcp_f32_e32 v37, v37
	v_pk_mul_f32 v[38:39], v[48:49], v[42:43] op_sel_hi:[0,1]
	v_pk_mul_f32 v[32:33], v[32:33], v[38:39]
	v_pk_mul_f32 v[24:25], v[28:29], v[24:25]
	v_cvt_pk_bf16_f32 v42, v32, v33
	v_pk_mul_f32 v[32:33], v[48:49], v[36:37] op_sel_hi:[0,1]
	v_pk_mul_f32 v[32:33], v[34:35], v[32:33]
	v_mul_f32_e32 v34, 0xbfb8aa3b, v140
	v_pk_mul_f32 v[36:37], v[28:29], v[34:35] op_sel_hi:[1,0]
	v_pk_mul_f32 v[28:29], v[30:31], v[34:35] op_sel_hi:[1,0]
	v_exp_f32_e32 v36, v36
	v_exp_f32_e32 v37, v37
	v_exp_f32_e32 v28, v28
	v_exp_f32_e32 v29, v29
	v_cvt_pk_bf16_f32 v43, v32, v33
	v_pk_add_f32 v[36:37], v[36:37], 1.0 op_sel_hi:[1,0]
	v_add_u32_e32 v32, 0x90, v167
	v_rcp_f32_e32 v36, v36
	v_rcp_f32_e32 v37, v37
	v_mad_i64_i32 v[32:33], s[14:15], v32, s59, v[112:113]
	v_pk_add_f32 v[28:29], v[28:29], 1.0 op_sel_hi:[1,0]
	v_lshl_add_u64 v[32:33], v[32:33], 0, v[114:115]
	v_rcp_f32_e32 v28, v28
	v_rcp_f32_e32 v29, v29
	global_store_dwordx4 v[32:33], v[40:43], off
	v_mul_f32_e32 v32, v140, v140
	v_pk_mul_f32 v[26:27], v[30:31], v[26:27]
	v_pk_mul_f32 v[30:31], v[32:33], v[36:37] op_sel_hi:[0,1]
	v_pk_mul_f32 v[24:25], v[24:25], v[30:31]
	v_pk_mul_f32 v[30:31], v[20:21], v[34:35] op_sel_hi:[1,0]
	v_pk_mul_f32 v[28:29], v[32:33], v[28:29] op_sel_hi:[0,1]
	v_exp_f32_e32 v30, v30
	v_exp_f32_e32 v31, v31
	v_pk_mul_f32 v[26:27], v[26:27], v[28:29]
	v_pk_mul_f32 v[28:29], v[22:23], v[34:35] op_sel_hi:[1,0]
	v_cvt_pk_bf16_f32 v24, v24, v25
	v_cvt_pk_bf16_f32 v25, v26, v27
	v_pk_add_f32 v[26:27], v[30:31], 1.0 op_sel_hi:[1,0]
	v_exp_f32_e32 v28, v28
	v_exp_f32_e32 v29, v29
	v_rcp_f32_e32 v26, v26
	v_rcp_f32_e32 v27, v27
	v_pk_mul_f32 v[16:17], v[20:21], v[16:17]
	v_pk_add_f32 v[20:21], v[28:29], 1.0 op_sel_hi:[1,0]
	v_pk_mul_f32 v[18:19], v[22:23], v[18:19]
	v_rcp_f32_e32 v20, v20
	v_rcp_f32_e32 v21, v21
	v_pk_mul_f32 v[22:23], v[32:33], v[26:27] op_sel_hi:[0,1]
	v_pk_mul_f32 v[16:17], v[16:17], v[22:23]
	v_pk_mul_f32 v[8:9], v[12:13], v[8:9]
	v_cvt_pk_bf16_f32 v26, v16, v17
	v_pk_mul_f32 v[16:17], v[32:33], v[20:21] op_sel_hi:[0,1]
	v_pk_mul_f32 v[16:17], v[18:19], v[16:17]
	v_mul_f32_e32 v18, 0xbfb8aa3b, v141
	v_pk_mul_f32 v[20:21], v[12:13], v[18:19] op_sel_hi:[1,0]
	v_pk_mul_f32 v[12:13], v[14:15], v[18:19] op_sel_hi:[1,0]
	v_exp_f32_e32 v20, v20
	v_exp_f32_e32 v21, v21
	v_exp_f32_e32 v12, v12
	v_exp_f32_e32 v13, v13
	v_cvt_pk_bf16_f32 v27, v16, v17
	v_pk_add_f32 v[20:21], v[20:21], 1.0 op_sel_hi:[1,0]
	v_add_u32_e32 v16, 0xa0, v167
	v_rcp_f32_e32 v20, v20
	v_rcp_f32_e32 v21, v21
	v_mad_i64_i32 v[16:17], s[14:15], v16, s59, v[112:113]
	v_pk_add_f32 v[12:13], v[12:13], 1.0 op_sel_hi:[1,0]
	v_lshl_add_u64 v[16:17], v[16:17], 0, v[114:115]
	v_rcp_f32_e32 v12, v12
	v_rcp_f32_e32 v13, v13
	global_store_dwordx4 v[16:17], v[24:27], off nt
	v_mul_f32_e32 v16, v141, v141
	v_pk_mul_f32 v[10:11], v[14:15], v[10:11]
	v_pk_mul_f32 v[14:15], v[16:17], v[20:21] op_sel_hi:[0,1]
	v_pk_mul_f32 v[8:9], v[8:9], v[14:15]
	v_pk_mul_f32 v[14:15], v[4:5], v[18:19] op_sel_hi:[1,0]
	v_pk_mul_f32 v[12:13], v[16:17], v[12:13] op_sel_hi:[0,1]
	v_exp_f32_e32 v14, v14
	v_exp_f32_e32 v15, v15
	v_pk_mul_f32 v[10:11], v[10:11], v[12:13]
	v_pk_mul_f32 v[12:13], v[6:7], v[18:19] op_sel_hi:[1,0]
	v_cvt_pk_bf16_f32 v8, v8, v9
	v_cvt_pk_bf16_f32 v9, v10, v11
	v_pk_add_f32 v[10:11], v[14:15], 1.0 op_sel_hi:[1,0]
	v_exp_f32_e32 v12, v12
	v_exp_f32_e32 v13, v13
	v_rcp_f32_e32 v10, v10
	v_rcp_f32_e32 v11, v11
	v_pk_mul_f32 v[0:1], v[4:5], v[0:1]
	v_pk_add_f32 v[4:5], v[12:13], 1.0 op_sel_hi:[1,0]
	v_pk_mul_f32 v[2:3], v[6:7], v[2:3]
	v_rcp_f32_e32 v4, v4
	v_rcp_f32_e32 v5, v5
	v_pk_mul_f32 v[6:7], v[16:17], v[10:11] op_sel_hi:[0,1]
	v_pk_mul_f32 v[0:1], v[0:1], v[6:7]
	s_andn2_b64 vcc, exec, s[8:9]
	v_cvt_pk_bf16_f32 v10, v0, v1
	v_pk_mul_f32 v[0:1], v[16:17], v[4:5] op_sel_hi:[0,1]
	v_pk_mul_f32 v[0:1], v[2:3], v[0:1]
	s_mov_b64 s[8:9], -1
	v_cvt_pk_bf16_f32 v11, v0, v1
	v_add_u32_e32 v0, 0xb0, v167
	v_mad_i64_i32 v[0:1], s[14:15], v0, s59, v[112:113]
	v_lshl_add_u64 v[0:1], v[0:1], 0, v[114:115]
	global_store_dwordx4 v[0:1], v[8:11], off
	s_cbranch_vccnz .LBB0_442
	s_andn2_b64 vcc, exec, s[0:1]
	s_cbranch_vccnz .LBB0_441
	s_barrier
	s_branch .LBB0_441
